# comb6 + in-proj K-loop only: early wave group gets own loop copy with vmcnt(8) deferred to end of MFMA block
# speedup vs baseline: 1.0087x; 1.0087x over previous
;     __host__ __device__ bool next(int i, Unit& u) const { const bool ok = StaticOrder::next(i >> 1, u); if (i & 1) { u.ka = D_INNER; u.nkt = D_ATT / BK; } else { u.ka = 0; u.nkt = D_INNER / BK; } return ok; }
;     __host__ __device__ bool next(int i, Unit& u) const { const long L = (long)i * G + c; if (L >= (long)nM * nS) return false; u.pm = (int)(L % nM); u.pn = 0; u.ka = (int)(L / nM) * kslab; u.nkt = kslab / BK; return true; }
;     __host__ __device__ bool next(int i, Unit& u) const { if (i > 0) return false; const int x = c & 7, j = c >> 3; u.pm = 16 * s + 4 * (x >> 1) + (j & 3); u.pn = 8 * (x & 1) + (j >> 2); u.ka = 0; u.nkt = nkt; return true; }
; #define PG8_LDA(dst, b, h) do { _Pragma("unroll") for (int m = 0; m < 4; ++m) _Pragma("unroll") for (int k = 0; k < 2; ++k) dst[m][k] = *(const LAS bf16x8*)(lds + PG8_SA(b, h) + aoff + m * 2048 + k * 1024); } while (0)
; template <class Epi, class Sched, bool ALIGN_EPI, class Hook = NoHook>
; __device__ __forceinline__ void gemm_phase(LAS unsigned char* lds, const Gemm g, const Sched& S, const Epi& E, const Hook& H = Hook()) {
;     ...
;         const bool has_next = S.next(ui + 1, nxt);
;         const char* nA = has_next ? (const char*)g.A + (size_t)nxt.pm * tA + (size_t)nxt.ka * 2 : cA; const char* nB = has_next ? (const char*)g.Bt + (size_t)nxt.pn * 2 * hB + (size_t)nxt.ka * 2 : cB;
;         const int nt = cur.nkt;
;         for (int tb = 0; tb < nt; tb += (Hook::ON ? Hook::SEG : nt)) {
;         const int te = Hook::ON ? tb + Hook::SEG : nt;
;         for (int t = tb; t < te; t += 2) {
;             const bool last = (t == nt - 2);
;             const char* a1 = cA + (size_t)(t + 1) * kstep;
;             const char* a2 = last ? nA : cA + (size_t)(t + 2) * kstep; const char* b2 = last ? nB : cB + (size_t)(t + 2) * kstep;
;             const char* a3 = a2 + kstep; const char* b3 = b2 + kstep;
;             if (last && has_next) S.a_ready(nxt);
;             PG8_LDB(B0, 0, 0); PG8_LDB(B1, 0, 1); PG8_SCHED; PG8_LDA(At, 0, 0); PG8_STAGE(PG8_SA(1, 1), a1 + hA, voffA);
;     ...
; #pragma unroll
;         for (int a = 0; a < 2; ++a)
; #pragma unroll
;             for (int b = 0; b < 2; ++b)
; #pragma unroll
;                 for (int m = 0; m < 4; ++m)
; #pragma unroll
;                     for (int n = 0; n < 2; ++n) acc[a][b][m][n] = (f32x4){0.f, 0.f, 0.f, 0.f};
;         cur = nxt; cA = nA; cB = nB; ++ui;
.LBB0_198:
	s_ashr_i32 s25, s24, 31
	s_lshl_b64 s[26:27], s[24:25], 21
	v_readlane_b32 s28, v255, 4
	v_readlane_b32 s29, v255, 5
	s_add_u32 s26, s28, s26
	s_addc_u32 s27, s29, s27
	s_and_b64 s[28:29], s[2:3], exec
	s_cselect_b32 s7, s27, s5
	s_cselect_b32 s8, s26, s4
	s_ashr_i32 s23, s22, 31
	s_lshl_b64 s[28:29], s[22:23], 21
	v_readlane_b32 s23, v254, 42
	s_add_u32 s28, s23, s28
	v_readlane_b32 s23, v254, 43
	s_addc_u32 s29, s23, s29
	s_and_b64 s[36:37], s[2:3], exec
	s_cselect_b32 s23, s29, s35
	s_cselect_b32 s25, s28, s34
	s_add_u32 s31, s34, 0x100
	v_mov_b32_e32 v2, 0
	s_addc_u32 s63, s35, 0
	s_mov_b32 s64, -2
	v_mov_b32_e32 v3, v2
	v_mov_b32_e32 v4, v2
	v_mov_b32_e32 v5, v2
	v_mov_b32_e32 v34, v2
	v_mov_b32_e32 v35, v2
	v_mov_b32_e32 v36, v2
	v_mov_b32_e32 v37, v2
	v_mov_b32_e32 v6, v2
	v_mov_b32_e32 v7, v2
	v_mov_b32_e32 v8, v2
	v_mov_b32_e32 v9, v2
	v_mov_b32_e32 v38, v2
	v_mov_b32_e32 v39, v2
	v_mov_b32_e32 v40, v2
	v_mov_b32_e32 v41, v2
	v_mov_b32_e32 v10, v2
	v_mov_b32_e32 v11, v2
	v_mov_b32_e32 v12, v2
	v_mov_b32_e32 v13, v2
	v_mov_b32_e32 v42, v2
	v_mov_b32_e32 v43, v2
	v_mov_b32_e32 v44, v2
	v_mov_b32_e32 v45, v2
	v_mov_b32_e32 v14, v2
	v_mov_b32_e32 v15, v2
	v_mov_b32_e32 v16, v2
	v_mov_b32_e32 v17, v2
	v_mov_b32_e32 v46, v2
	v_mov_b32_e32 v47, v2
	v_mov_b32_e32 v48, v2
	v_mov_b32_e32 v49, v2
	v_mov_b32_e32 v66, v2
	v_mov_b32_e32 v67, v2
	v_mov_b32_e32 v68, v2
	v_mov_b32_e32 v69, v2
	v_mov_b32_e32 v98, v2
	v_mov_b32_e32 v99, v2
	v_mov_b32_e32 v100, v2
	v_mov_b32_e32 v101, v2
	v_mov_b32_e32 v70, v2
	v_mov_b32_e32 v71, v2
	v_mov_b32_e32 v72, v2
	v_mov_b32_e32 v73, v2
	v_mov_b32_e32 v102, v2
	v_mov_b32_e32 v103, v2
	v_mov_b32_e32 v104, v2
	v_mov_b32_e32 v105, v2
	v_mov_b32_e32 v74, v2
	v_mov_b32_e32 v75, v2
	v_mov_b32_e32 v76, v2
	v_mov_b32_e32 v77, v2
	v_mov_b32_e32 v106, v2
	v_mov_b32_e32 v107, v2
	v_mov_b32_e32 v108, v2
	v_mov_b32_e32 v109, v2
	v_mov_b32_e32 v78, v2
	v_mov_b32_e32 v79, v2
	v_mov_b32_e32 v80, v2
	v_mov_b32_e32 v81, v2
	v_mov_b32_e32 v110, v2
	v_mov_b32_e32 v111, v2
	v_mov_b32_e32 v112, v2
	v_mov_b32_e32 v113, v2
	v_mov_b32_e32 v18, v2
	v_mov_b32_e32 v19, v2
	v_mov_b32_e32 v20, v2
	v_mov_b32_e32 v21, v2
	v_mov_b32_e32 v50, v2
	v_mov_b32_e32 v51, v2
	v_mov_b32_e32 v52, v2
	v_mov_b32_e32 v53, v2
	s_waitcnt vmcnt(0)
	v_mov_b32_e32 v22, v2
	v_mov_b32_e32 v23, v2
	v_mov_b32_e32 v24, v2
	v_mov_b32_e32 v25, v2
	v_mov_b32_e32 v54, v2
	v_mov_b32_e32 v55, v2
	v_mov_b32_e32 v56, v2
	v_mov_b32_e32 v57, v2
	v_mov_b32_e32 v26, v2
	v_mov_b32_e32 v27, v2
	v_mov_b32_e32 v28, v2
	v_mov_b32_e32 v29, v2
	v_mov_b32_e32 v58, v2
	v_mov_b32_e32 v59, v2
	v_mov_b32_e32 v60, v2
	v_mov_b32_e32 v61, v2
	v_mov_b32_e32 v30, v2
	v_mov_b32_e32 v31, v2
	v_mov_b32_e32 v32, v2
	v_mov_b32_e32 v33, v2
	v_mov_b32_e32 v62, v2
	v_mov_b32_e32 v63, v2
	v_mov_b32_e32 v64, v2
	v_mov_b32_e32 v65, v2
	v_mov_b32_e32 v82, v2
	v_mov_b32_e32 v83, v2
	v_mov_b32_e32 v84, v2
	v_mov_b32_e32 v85, v2
	v_mov_b32_e32 v114, v2
	v_mov_b32_e32 v115, v2
	v_mov_b32_e32 v116, v2
	v_mov_b32_e32 v117, v2
	v_mov_b32_e32 v86, v2
	v_mov_b32_e32 v87, v2
	v_mov_b32_e32 v88, v2
	v_mov_b32_e32 v89, v2
	v_mov_b32_e32 v118, v2
	v_mov_b32_e32 v119, v2
	v_mov_b32_e32 v120, v2
	v_mov_b32_e32 v121, v2
	v_mov_b32_e32 v90, v2
	v_mov_b32_e32 v91, v2
	v_mov_b32_e32 v92, v2
	v_mov_b32_e32 v93, v2
	v_mov_b32_e32 v122, v2
	v_mov_b32_e32 v123, v2
	v_mov_b32_e32 v124, v2
	v_mov_b32_e32 v125, v2
	v_mov_b32_e32 v94, v2
	v_mov_b32_e32 v95, v2
	v_mov_b32_e32 v96, v2
	v_mov_b32_e32 v97, v2
	v_mov_b32_e32 v126, v2
	v_mov_b32_e32 v127, v2
	v_mov_b32_e32 v128, v2
	v_mov_b32_e32 v129, v2
	s_and_b64 vcc, exec, s[18:19]
	s_cbranch_vccz .Lmy_d199B
.LBB0_199:
	ds_read_b128 v[130:133], v217
	ds_read_b128 v[134:137], v217 offset:1024
	s_add_u32 s34, s4, 0x100
	s_addc_u32 s35, s5, 0
	s_cmp_eq_u32 s64, 60
	s_cselect_b32 s39, s7, s35
	s_cselect_b32 s38, s8, s34
	s_cselect_b32 s37, s23, s63
	s_cselect_b32 s36, s25, s31
	s_add_i32 m0, s40, 0xc000
	s_nop 0
	global_load_lds_dwordx4 v172, s[4:5]
	ds_read_b128 v[138:141], v217 offset:2048
	ds_read_b128 v[142:145], v217 offset:3072
	ds_read_b128 v[146:149], v218
	ds_read_b128 v[150:153], v218 offset:1024
	ds_read_b128 v[154:157], v218 offset:2048
	ds_read_b128 v[158:161], v218 offset:3072
	ds_read_b128 v[180:183], v219
	s_add_i32 m0, s40, 0xe000
	s_nop 0
	global_load_lds_dwordx4 v174, s[4:5]
	ds_read_b128 v[184:187], v219 offset:1024
	ds_read_b128 v[188:191], v219 offset:2048
	ds_read_b128 v[192:195], v219 offset:3072
	ds_read_b128 v[196:199], v219 offset:4096
	ds_read_b128 v[200:203], v219 offset:5120
	ds_read_b128 v[204:207], v219 offset:6144
	ds_read_b128 v[208:211], v219 offset:7168
	s_waitcnt lgkmcnt(0)
	s_barrier
; #define PG8_STAGE(bufoff, gbase, voff) do { _Pragma("unroll") for (int _i = 0; _i < 2; ++_i) \
;         __builtin_amdgcn_global_load_lds((const unsigned*)((const char*)(gbase) + (voff)[_i]), (LAS unsigned*)(lds + (bufoff) + ldsw + _i * 8192), 16, 0, 0); } while (0)
; #define PG8_LDA(dst, b, h) do { _Pragma("unroll") for (int m = 0; m < 4; ++m) _Pragma("unroll") for (int k = 0; k < 2; ++k) dst[m][k] = *(const LAS bf16x8*)(lds + PG8_SA(b, h) + aoff + m * 2048 + k * 1024); } while (0)
; #define PG8_MMA(ai, bj, At, Bt) do { __builtin_amdgcn_s_setprio(1); _Pragma("unroll") for (int m = 0; m < 4; ++m) _Pragma("unroll") for (int n = 0; n < 2; ++n) _Pragma("unroll") for (int k = 0; k < 2; ++k) \
;         acc[ai][bj][m][n] = __builtin_amdgcn_mfma_f32_16x16x32_bf16(Bt[n][k], At[m][k], acc[ai][bj][m][n], 0, 0, 0); __builtin_amdgcn_s_setprio(0); } while (0)
; #define PG8_WAIT_V(n) asm volatile("s_waitcnt vmcnt(" #n ")" ::: "memory")
; #define PG8_WAIT_L(n) asm volatile("s_waitcnt lgkmcnt(" #n ")" ::: "memory")
; #define PG8_BAR __builtin_amdgcn_s_barrier()
; #define PG8_SCHED __builtin_amdgcn_sched_barrier(0)
; template <class Epi, class Sched, bool ALIGN_EPI, class Hook = NoHook>
; __device__ __forceinline__ void gemm_phase(LAS unsigned char* lds, const Gemm g, const Sched& S, const Epi& E, const Hook& H = Hook()) {
;     ...
;             PG8_WAIT_V(8); PG8_WAIT_L(0); PG8_BAR; PG8_MMA(0, 0, At, B0); PG8_MMA(0, 1, At, B1); PG8_BAR; PG8_SCHED;
;             PG8_LDA(At, 0, 1); PG8_STAGE(PG8_SB(0, 0), b2, voffB); PG8_STAGE(PG8_SB(0, 1), b2 + hB, voffB); PG8_STAGE(PG8_SA(0, 0), a2, voffA);
;             PG8_WAIT_V(8); PG8_WAIT_L(0); PG8_BAR; PG8_MMA(1, 0, At, B0); PG8_MMA(1, 1, At, B1); PG8_BAR; PG8_SCHED;
	s_setprio 1
	s_waitcnt lgkmcnt(0)
	v_mfma_f32_16x16x32_bf16 v[126:129], v[130:133], v[180:183], v[126:129]
	v_mfma_f32_16x16x32_bf16 v[94:97], v[138:141], v[180:183], v[94:97]
	v_mfma_f32_16x16x32_bf16 v[122:125], v[130:133], v[188:191], v[122:125]
	v_mfma_f32_16x16x32_bf16 v[90:93], v[138:141], v[188:191], v[90:93]
	v_mfma_f32_16x16x32_bf16 v[118:121], v[130:133], v[196:199], v[118:121]
	v_mfma_f32_16x16x32_bf16 v[86:89], v[138:141], v[196:199], v[86:89]
	v_mfma_f32_16x16x32_bf16 v[114:117], v[130:133], v[204:207], v[114:117]
	v_mfma_f32_16x16x32_bf16 v[82:85], v[138:141], v[204:207], v[82:85]
	v_mfma_f32_16x16x32_bf16 v[126:129], v[134:137], v[184:187], v[126:129]
	v_mfma_f32_16x16x32_bf16 v[94:97], v[142:145], v[184:187], v[94:97]
	v_mfma_f32_16x16x32_bf16 v[122:125], v[134:137], v[192:195], v[122:125]
	v_mfma_f32_16x16x32_bf16 v[90:93], v[142:145], v[192:195], v[90:93]
	v_mfma_f32_16x16x32_bf16 v[118:121], v[134:137], v[200:203], v[118:121]
	v_mfma_f32_16x16x32_bf16 v[86:89], v[142:145], v[200:203], v[86:89]
	v_mfma_f32_16x16x32_bf16 v[114:117], v[134:137], v[208:211], v[114:117]
	v_mfma_f32_16x16x32_bf16 v[82:85], v[142:145], v[208:211], v[82:85]
	s_setprio 0
	s_setprio 1
	v_mfma_f32_16x16x32_bf16 v[62:65], v[146:149], v[180:183], v[62:65]
	v_mfma_f32_16x16x32_bf16 v[30:33], v[154:157], v[180:183], v[30:33]
	v_mfma_f32_16x16x32_bf16 v[58:61], v[146:149], v[188:191], v[58:61]
	v_mfma_f32_16x16x32_bf16 v[26:29], v[154:157], v[188:191], v[26:29]
	v_mfma_f32_16x16x32_bf16 v[54:57], v[146:149], v[196:199], v[54:57]
	v_mfma_f32_16x16x32_bf16 v[22:25], v[154:157], v[196:199], v[22:25]
	v_mfma_f32_16x16x32_bf16 v[50:53], v[146:149], v[204:207], v[50:53]
	v_mfma_f32_16x16x32_bf16 v[18:21], v[154:157], v[204:207], v[18:21]
	v_mfma_f32_16x16x32_bf16 v[62:65], v[150:153], v[184:187], v[62:65]
	v_mfma_f32_16x16x32_bf16 v[30:33], v[158:161], v[184:187], v[30:33]
	v_mfma_f32_16x16x32_bf16 v[58:61], v[150:153], v[192:195], v[58:61]
	v_mfma_f32_16x16x32_bf16 v[26:29], v[158:161], v[192:195], v[26:29]
	v_mfma_f32_16x16x32_bf16 v[54:57], v[150:153], v[200:203], v[54:57]
	v_mfma_f32_16x16x32_bf16 v[22:25], v[158:161], v[200:203], v[22:25]
	v_mfma_f32_16x16x32_bf16 v[50:53], v[150:153], v[208:211], v[50:53]
	v_mfma_f32_16x16x32_bf16 v[18:21], v[158:161], v[208:211], v[18:21]
	s_setprio 0
	s_waitcnt vmcnt(8)
	s_barrier
	s_add_i32 s4, s59, s21
	s_mov_b32 m0, s4
	ds_read_b128 v[180:183], v219 offset:16384
	ds_read_b128 v[184:187], v219 offset:17408
	global_load_lds_dwordx4 v164, s[36:37]
	ds_read_b128 v[188:191], v219 offset:18432
	s_add_i32 m0, s4, 0x2000
	s_add_u32 s4, s36, 0x100000
	s_addc_u32 s5, s37, 0
	s_add_i32 s65, s60, s21
	global_load_lds_dwordx4 v168, s[36:37]
	ds_read_b128 v[192:195], v219 offset:19456
	s_mov_b32 m0, s65
	s_nop 0
	global_load_lds_dwordx4 v164, s[4:5]
	ds_read_b128 v[196:199], v219 offset:20480
	s_add_i32 m0, s65, 0x2000
	s_nop 0
	global_load_lds_dwordx4 v168, s[4:5]
	ds_read_b128 v[200:203], v219 offset:21504
	s_mov_b32 m0, s40
	s_nop 0
	global_load_lds_dwordx4 v162, s[38:39]
	ds_read_b128 v[204:207], v219 offset:22528
	s_mov_b32 m0, s41
	s_nop 0
	global_load_lds_dwordx4 v166, s[38:39]
	ds_read_b128 v[208:211], v219 offset:23552
	s_waitcnt lgkmcnt(0)
	s_barrier
	s_setprio 1
	s_waitcnt lgkmcnt(0)
	v_mfma_f32_16x16x32_bf16 v[110:113], v[130:133], v[180:183], v[110:113]
	v_mfma_f32_16x16x32_bf16 v[78:81], v[138:141], v[180:183], v[78:81]
	v_mfma_f32_16x16x32_bf16 v[106:109], v[130:133], v[188:191], v[106:109]
	v_mfma_f32_16x16x32_bf16 v[74:77], v[138:141], v[188:191], v[74:77]
	v_mfma_f32_16x16x32_bf16 v[102:105], v[130:133], v[196:199], v[102:105]
	v_mfma_f32_16x16x32_bf16 v[70:73], v[138:141], v[196:199], v[70:73]
	v_mfma_f32_16x16x32_bf16 v[98:101], v[130:133], v[204:207], v[98:101]
	v_mfma_f32_16x16x32_bf16 v[66:69], v[138:141], v[204:207], v[66:69]
	v_mfma_f32_16x16x32_bf16 v[110:113], v[134:137], v[184:187], v[110:113]
	v_mfma_f32_16x16x32_bf16 v[78:81], v[142:145], v[184:187], v[78:81]
	v_mfma_f32_16x16x32_bf16 v[106:109], v[134:137], v[192:195], v[106:109]
	v_mfma_f32_16x16x32_bf16 v[74:77], v[142:145], v[192:195], v[74:77]
	v_mfma_f32_16x16x32_bf16 v[102:105], v[134:137], v[200:203], v[102:105]
	v_mfma_f32_16x16x32_bf16 v[70:73], v[142:145], v[200:203], v[70:73]
	v_mfma_f32_16x16x32_bf16 v[98:101], v[134:137], v[208:211], v[98:101]
	v_mfma_f32_16x16x32_bf16 v[66:69], v[142:145], v[208:211], v[66:69]
	s_setprio 0
	s_setprio 1
	v_mfma_f32_16x16x32_bf16 v[46:49], v[146:149], v[180:183], v[46:49]
	v_mfma_f32_16x16x32_bf16 v[14:17], v[154:157], v[180:183], v[14:17]
	v_mfma_f32_16x16x32_bf16 v[42:45], v[146:149], v[188:191], v[42:45]
	v_mfma_f32_16x16x32_bf16 v[10:13], v[154:157], v[188:191], v[10:13]
	v_mfma_f32_16x16x32_bf16 v[38:41], v[146:149], v[196:199], v[38:41]
	v_mfma_f32_16x16x32_bf16 v[6:9], v[154:157], v[196:199], v[6:9]
	v_mfma_f32_16x16x32_bf16 v[34:37], v[146:149], v[204:207], v[34:37]
	v_mfma_f32_16x16x32_bf16 v[2:5], v[154:157], v[204:207], v[2:5]
	v_mfma_f32_16x16x32_bf16 v[46:49], v[150:153], v[184:187], v[46:49]
	v_mfma_f32_16x16x32_bf16 v[14:17], v[158:161], v[184:187], v[14:17]
	v_mfma_f32_16x16x32_bf16 v[42:45], v[150:153], v[192:195], v[42:45]
	v_mfma_f32_16x16x32_bf16 v[10:13], v[158:161], v[192:195], v[10:13]
	v_mfma_f32_16x16x32_bf16 v[38:41], v[150:153], v[200:203], v[38:41]
	v_mfma_f32_16x16x32_bf16 v[6:9], v[158:161], v[200:203], v[6:9]
	v_mfma_f32_16x16x32_bf16 v[34:37], v[150:153], v[208:211], v[34:37]
	v_mfma_f32_16x16x32_bf16 v[2:5], v[158:161], v[208:211], v[2:5]
	s_setprio 0
	s_waitcnt vmcnt(8)
	s_barrier
; #define PG8_STAGE(bufoff, gbase, voff) do { _Pragma("unroll") for (int _i = 0; _i < 2; ++_i) \
;         __builtin_amdgcn_global_load_lds((const unsigned*)((const char*)(gbase) + (voff)[_i]), (LAS unsigned*)(lds + (bufoff) + ldsw + _i * 8192), 16, 0, 0); } while (0)
; #define PG8_LDA(dst, b, h) do { _Pragma("unroll") for (int m = 0; m < 4; ++m) _Pragma("unroll") for (int k = 0; k < 2; ++k) dst[m][k] = *(const LAS bf16x8*)(lds + PG8_SA(b, h) + aoff + m * 2048 + k * 1024); } while (0)
; #define PG8_LDB(dst, b, h) do { _Pragma("unroll") for (int n = 0; n < 2; ++n) _Pragma("unroll") for (int k = 0; k < 2; ++k) dst[n][k] = *(const LAS bf16x8*)(lds + PG8_SB(b, h) + boff + n * 2048 + k * 1024); } while (0)
; #define PG8_MMA(ai, bj, At, Bt) do { __builtin_amdgcn_s_setprio(1); _Pragma("unroll") for (int m = 0; m < 4; ++m) _Pragma("unroll") for (int n = 0; n < 2; ++n) _Pragma("unroll") for (int k = 0; k < 2; ++k) \
;         acc[ai][bj][m][n] = __builtin_amdgcn_mfma_f32_16x16x32_bf16(Bt[n][k], At[m][k], acc[ai][bj][m][n], 0, 0, 0); __builtin_amdgcn_s_setprio(0); } while (0)
; #define PG8_WAIT_V(n) asm volatile("s_waitcnt vmcnt(" #n ")" ::: "memory")
; #define PG8_WAIT_L(n) asm volatile("s_waitcnt lgkmcnt(" #n ")" ::: "memory")
; #define PG8_BAR __builtin_amdgcn_s_barrier()
; #define PG8_SCHED __builtin_amdgcn_sched_barrier(0)
; template <class Epi, class Sched, bool ALIGN_EPI, class Hook = NoHook>
; __device__ __forceinline__ void gemm_phase(LAS unsigned char* lds, const Gemm g, const Sched& S, const Epi& E, const Hook& H = Hook()) {
;     ...
;             PG8_LDB(B0, 1, 0); PG8_LDB(B1, 1, 1); PG8_SCHED; PG8_LDA(At, 1, 0); PG8_STAGE(PG8_SA(0, 1), a2 + hA, voffA);
;             PG8_WAIT_V(8); PG8_WAIT_L(0); PG8_BAR; PG8_MMA(0, 0, At, B0); PG8_MMA(0, 1, At, B1); PG8_BAR; PG8_SCHED;
;             PG8_LDA(At, 1, 1); PG8_STAGE(PG8_SB(1, 0), b3, voffB); PG8_STAGE(PG8_SB(1, 1), b3 + hB, voffB); PG8_STAGE(PG8_SA(1, 0), a3, voffA);
;             PG8_WAIT_V(8); PG8_WAIT_L(0); PG8_BAR; PG8_MMA(1, 0, At, B0); PG8_MMA(1, 1, At, B1); PG8_BAR; PG8_SCHED;
;         }
	s_add_i32 s65, 0, 0x18000
	s_add_i32 s66, 0, 0x1c000
	v_add_u32_e32 v142, s65, v213
	v_add_u32_e32 v158, s66, v213
	ds_read_b128 v[130:133], v142
	ds_read_b128 v[134:137], v142 offset:1024
	s_add_u32 s4, s38, 0x8000
	s_addc_u32 s5, s39, 0
	s_mov_b32 m0, s42
	s_nop 0
	global_load_lds_dwordx4 v162, s[4:5]
	ds_read_b128 v[138:141], v142 offset:2048
	ds_read_b128 v[142:145], v142 offset:3072
	ds_read_b128 v[146:149], v158
	ds_read_b128 v[150:153], v158 offset:1024
	ds_read_b128 v[154:157], v158 offset:2048
	ds_read_b128 v[158:161], v158 offset:3072
	ds_read_b128 v[180:183], v219 offset:32768
	s_mov_b32 m0, s43
	s_nop 0
	global_load_lds_dwordx4 v166, s[4:5]
	ds_read_b128 v[184:187], v219 offset:33792
	ds_read_b128 v[188:191], v219 offset:34816
	ds_read_b128 v[192:195], v219 offset:35840
	ds_read_b128 v[196:199], v219 offset:36864
	ds_read_b128 v[200:203], v219 offset:37888
	ds_read_b128 v[204:207], v219 offset:38912
	ds_read_b128 v[208:211], v219 offset:39936
	s_waitcnt lgkmcnt(0)
	s_barrier
	s_setprio 1
	s_waitcnt lgkmcnt(0)
	v_mfma_f32_16x16x32_bf16 v[126:129], v[130:133], v[180:183], v[126:129]
	v_mfma_f32_16x16x32_bf16 v[94:97], v[138:141], v[180:183], v[94:97]
	v_mfma_f32_16x16x32_bf16 v[122:125], v[130:133], v[188:191], v[122:125]
	v_mfma_f32_16x16x32_bf16 v[90:93], v[138:141], v[188:191], v[90:93]
	v_mfma_f32_16x16x32_bf16 v[118:121], v[130:133], v[196:199], v[118:121]
	v_mfma_f32_16x16x32_bf16 v[86:89], v[138:141], v[196:199], v[86:89]
	v_mfma_f32_16x16x32_bf16 v[114:117], v[130:133], v[204:207], v[114:117]
	v_mfma_f32_16x16x32_bf16 v[82:85], v[138:141], v[204:207], v[82:85]
	v_mfma_f32_16x16x32_bf16 v[126:129], v[134:137], v[184:187], v[126:129]
	v_mfma_f32_16x16x32_bf16 v[94:97], v[142:145], v[184:187], v[94:97]
	v_mfma_f32_16x16x32_bf16 v[122:125], v[134:137], v[192:195], v[122:125]
	v_mfma_f32_16x16x32_bf16 v[90:93], v[142:145], v[192:195], v[90:93]
	v_mfma_f32_16x16x32_bf16 v[118:121], v[134:137], v[200:203], v[118:121]
	v_mfma_f32_16x16x32_bf16 v[86:89], v[142:145], v[200:203], v[86:89]
	v_mfma_f32_16x16x32_bf16 v[114:117], v[134:137], v[208:211], v[114:117]
	v_mfma_f32_16x16x32_bf16 v[82:85], v[142:145], v[208:211], v[82:85]
	s_setprio 0
	s_setprio 1
	v_mfma_f32_16x16x32_bf16 v[62:65], v[146:149], v[180:183], v[62:65]
	v_mfma_f32_16x16x32_bf16 v[30:33], v[154:157], v[180:183], v[30:33]
	v_mfma_f32_16x16x32_bf16 v[58:61], v[146:149], v[188:191], v[58:61]
	v_mfma_f32_16x16x32_bf16 v[26:29], v[154:157], v[188:191], v[26:29]
	v_mfma_f32_16x16x32_bf16 v[54:57], v[146:149], v[196:199], v[54:57]
	v_mfma_f32_16x16x32_bf16 v[22:25], v[154:157], v[196:199], v[22:25]
	v_mfma_f32_16x16x32_bf16 v[50:53], v[146:149], v[204:207], v[50:53]
	v_mfma_f32_16x16x32_bf16 v[18:21], v[154:157], v[204:207], v[18:21]
	v_mfma_f32_16x16x32_bf16 v[62:65], v[150:153], v[184:187], v[62:65]
	v_mfma_f32_16x16x32_bf16 v[30:33], v[158:161], v[184:187], v[30:33]
	v_mfma_f32_16x16x32_bf16 v[58:61], v[150:153], v[192:195], v[58:61]
	v_mfma_f32_16x16x32_bf16 v[26:29], v[158:161], v[192:195], v[26:29]
	v_mfma_f32_16x16x32_bf16 v[54:57], v[150:153], v[200:203], v[54:57]
	v_mfma_f32_16x16x32_bf16 v[22:25], v[158:161], v[200:203], v[22:25]
	v_mfma_f32_16x16x32_bf16 v[50:53], v[150:153], v[208:211], v[50:53]
	v_mfma_f32_16x16x32_bf16 v[18:21], v[158:161], v[208:211], v[18:21]
	s_setprio 0
	s_waitcnt vmcnt(8)
	s_barrier
	s_add_i32 s4, s65, s21
	s_add_u32 s68, s36, s14
	s_addc_u32 s69, s37, s15
	s_mov_b32 m0, s4
	ds_read_b128 v[180:183], v219 offset:49152
	ds_read_b128 v[184:187], v219 offset:50176
	global_load_lds_dwordx4 v164, s[68:69]
	ds_read_b128 v[188:191], v219 offset:51200
	s_add_i32 m0, s4, 0x2000
	s_add_u32 s4, s36, 0x100080
	s_addc_u32 s5, s37, 0
	s_add_i32 s36, s66, s21
	global_load_lds_dwordx4 v168, s[68:69]
	ds_read_b128 v[192:195], v219 offset:52224
	s_mov_b32 m0, s36
	s_nop 0
	global_load_lds_dwordx4 v164, s[4:5]
	ds_read_b128 v[196:199], v219 offset:53248
	s_add_i32 m0, s36, 0x2000
	s_nop 0
	global_load_lds_dwordx4 v168, s[4:5]
	ds_read_b128 v[200:203], v219 offset:54272
	s_add_u32 s70, s38, s14
	s_addc_u32 s71, s39, s15
	s_mov_b32 m0, s51
	s_nop 0
	global_load_lds_dwordx4 v162, s[70:71]
	ds_read_b128 v[204:207], v219 offset:55296
	s_mov_b32 m0, s52
	s_nop 0
	global_load_lds_dwordx4 v166, s[70:71]
	ds_read_b128 v[208:211], v219 offset:56320
	s_waitcnt lgkmcnt(0)
	s_barrier
	s_setprio 1
	s_waitcnt lgkmcnt(0)
	v_mfma_f32_16x16x32_bf16 v[110:113], v[130:133], v[180:183], v[110:113]
	v_mfma_f32_16x16x32_bf16 v[78:81], v[138:141], v[180:183], v[78:81]
	v_mfma_f32_16x16x32_bf16 v[106:109], v[130:133], v[188:191], v[106:109]
	v_mfma_f32_16x16x32_bf16 v[74:77], v[138:141], v[188:191], v[74:77]
	v_mfma_f32_16x16x32_bf16 v[102:105], v[130:133], v[196:199], v[102:105]
	v_mfma_f32_16x16x32_bf16 v[70:73], v[138:141], v[196:199], v[70:73]
	v_mfma_f32_16x16x32_bf16 v[98:101], v[130:133], v[204:207], v[98:101]
	v_mfma_f32_16x16x32_bf16 v[66:69], v[138:141], v[204:207], v[66:69]
	v_mfma_f32_16x16x32_bf16 v[110:113], v[134:137], v[184:187], v[110:113]
	v_mfma_f32_16x16x32_bf16 v[78:81], v[142:145], v[184:187], v[78:81]
	v_mfma_f32_16x16x32_bf16 v[106:109], v[134:137], v[192:195], v[106:109]
	v_mfma_f32_16x16x32_bf16 v[74:77], v[142:145], v[192:195], v[74:77]
	v_mfma_f32_16x16x32_bf16 v[102:105], v[134:137], v[200:203], v[102:105]
	v_mfma_f32_16x16x32_bf16 v[70:73], v[142:145], v[200:203], v[70:73]
	v_mfma_f32_16x16x32_bf16 v[98:101], v[134:137], v[208:211], v[98:101]
	v_mfma_f32_16x16x32_bf16 v[66:69], v[142:145], v[208:211], v[66:69]
	s_setprio 0
	s_setprio 1
	v_mfma_f32_16x16x32_bf16 v[46:49], v[146:149], v[180:183], v[46:49]
	v_mfma_f32_16x16x32_bf16 v[14:17], v[154:157], v[180:183], v[14:17]
	v_mfma_f32_16x16x32_bf16 v[42:45], v[146:149], v[188:191], v[42:45]
	v_mfma_f32_16x16x32_bf16 v[10:13], v[154:157], v[188:191], v[10:13]
	v_mfma_f32_16x16x32_bf16 v[38:41], v[146:149], v[196:199], v[38:41]
	v_mfma_f32_16x16x32_bf16 v[6:9], v[154:157], v[196:199], v[6:9]
	v_mfma_f32_16x16x32_bf16 v[34:37], v[146:149], v[204:207], v[34:37]
	v_mfma_f32_16x16x32_bf16 v[2:5], v[154:157], v[204:207], v[2:5]
	v_mfma_f32_16x16x32_bf16 v[46:49], v[150:153], v[184:187], v[46:49]
	v_mfma_f32_16x16x32_bf16 v[14:17], v[158:161], v[184:187], v[14:17]
	v_mfma_f32_16x16x32_bf16 v[42:45], v[150:153], v[192:195], v[42:45]
	v_mfma_f32_16x16x32_bf16 v[10:13], v[158:161], v[192:195], v[10:13]
	v_mfma_f32_16x16x32_bf16 v[38:41], v[150:153], v[200:203], v[38:41]
	v_mfma_f32_16x16x32_bf16 v[6:9], v[158:161], v[200:203], v[6:9]
	v_mfma_f32_16x16x32_bf16 v[34:37], v[150:153], v[208:211], v[34:37]
	v_mfma_f32_16x16x32_bf16 v[2:5], v[158:161], v[208:211], v[2:5]
	s_setprio 0
	s_waitcnt vmcnt(8)
	s_barrier
	s_add_i32 s64, s64, 2
	s_add_u32 s31, s31, 0x100
	s_addc_u32 s63, s63, 0
	s_cmp_gt_u32 s64, 61
	s_mov_b64 s[4:5], s[34:35]
	s_cbranch_scc0 .LBB0_199
	s_branch .Lmy_d199X
; #define PG8_STAGE(bufoff, gbase, voff) do { _Pragma("unroll") for (int _i = 0; _i < 2; ++_i) \
;         __builtin_amdgcn_global_load_lds((const unsigned*)((const char*)(gbase) + (voff)[_i]), (LAS unsigned*)(lds + (bufoff) + ldsw + _i * 8192), 16, 0, 0); } while (0)
; #define PG8_LDA(dst, b, h) do { _Pragma("unroll") for (int m = 0; m < 4; ++m) _Pragma("unroll") for (int k = 0; k < 2; ++k) dst[m][k] = *(const LAS bf16x8*)(lds + PG8_SA(b, h) + aoff + m * 2048 + k * 1024); } while (0)
; #define PG8_LDB(dst, b, h) do { _Pragma("unroll") for (int n = 0; n < 2; ++n) _Pragma("unroll") for (int k = 0; k < 2; ++k) dst[n][k] = *(const LAS bf16x8*)(lds + PG8_SB(b, h) + boff + n * 2048 + k * 1024); } while (0)
; #define PG8_MMA(ai, bj, At, Bt) do { __builtin_amdgcn_s_setprio(1); _Pragma("unroll") for (int m = 0; m < 4; ++m) _Pragma("unroll") for (int n = 0; n < 2; ++n) _Pragma("unroll") for (int k = 0; k < 2; ++k) \
;         acc[ai][bj][m][n] = __builtin_amdgcn_mfma_f32_16x16x32_bf16(Bt[n][k], At[m][k], acc[ai][bj][m][n], 0, 0, 0); __builtin_amdgcn_s_setprio(0); } while (0)
; #define PG8_WAIT_V(n) asm volatile("s_waitcnt vmcnt(" #n ")" ::: "memory")
; #define PG8_WAIT_L(n) asm volatile("s_waitcnt lgkmcnt(" #n ")" ::: "memory")
; #define PG8_BAR __builtin_amdgcn_s_barrier()
; template <class Epi, class Sched, bool ALIGN_EPI, class Hook = NoHook>
; __device__ __forceinline__ void gemm_phase(LAS unsigned char* lds, const Gemm g, const Sched& S, const Epi& E, const Hook& H = Hook()) {
;     ...
;             const bool last = (t == nt - 2);
;             const char* a1 = cA + (size_t)(t + 1) * kstep;
;             const char* a2 = last ? nA : cA + (size_t)(t + 2) * kstep; const char* b2 = last ? nB : cB + (size_t)(t + 2) * kstep;
;             const char* a3 = a2 + kstep; const char* b3 = b2 + kstep;
;             if (last && has_next) S.a_ready(nxt);
;             PG8_LDB(B0, 0, 0); PG8_LDB(B1, 0, 1); PG8_SCHED; PG8_LDA(At, 0, 0); PG8_STAGE(PG8_SA(1, 1), a1 + hA, voffA);
;             PG8_WAIT_V(8); PG8_WAIT_L(0); PG8_BAR; PG8_MMA(0, 0, At, B0); PG8_MMA(0, 1, At, B1); PG8_BAR; PG8_SCHED;
;             PG8_LDA(At, 0, 1); PG8_STAGE(PG8_SB(0, 0), b2, voffB); PG8_STAGE(PG8_SB(0, 1), b2 + hB, voffB); PG8_STAGE(PG8_SA(0, 0), a2, voffA);
;             PG8_WAIT_V(8); PG8_WAIT_L(0); PG8_BAR; PG8_MMA(1, 0, At, B0); PG8_MMA(1, 1, At, B1); PG8_BAR; PG8_SCHED;
.Lmy_d199B:
	ds_read_b128 v[130:133], v217
	ds_read_b128 v[134:137], v217 offset:1024
	s_add_u32 s34, s4, 0x100
	s_addc_u32 s35, s5, 0
	s_cmp_eq_u32 s64, 60
	s_cselect_b32 s39, s7, s35
	s_cselect_b32 s38, s8, s34
	s_cselect_b32 s37, s23, s63
	s_cselect_b32 s36, s25, s31
	s_add_i32 m0, s40, 0xc000
	s_nop 0
	global_load_lds_dwordx4 v172, s[4:5]
	ds_read_b128 v[138:141], v217 offset:2048
	ds_read_b128 v[142:145], v217 offset:3072
	ds_read_b128 v[146:149], v218
	ds_read_b128 v[150:153], v218 offset:1024
	ds_read_b128 v[154:157], v218 offset:2048
	ds_read_b128 v[158:161], v218 offset:3072
	ds_read_b128 v[180:183], v219
	s_add_i32 m0, s40, 0xe000
	s_nop 0
	global_load_lds_dwordx4 v174, s[4:5]
	ds_read_b128 v[184:187], v219 offset:1024
	ds_read_b128 v[188:191], v219 offset:2048
	ds_read_b128 v[192:195], v219 offset:3072
	ds_read_b128 v[196:199], v219 offset:4096
	ds_read_b128 v[200:203], v219 offset:5120
	ds_read_b128 v[204:207], v219 offset:6144
	ds_read_b128 v[208:211], v219 offset:7168
	s_waitcnt vmcnt(8)
	s_waitcnt lgkmcnt(0)
	s_barrier
	s_setprio 1
	s_waitcnt lgkmcnt(0)
	v_mfma_f32_16x16x32_bf16 v[126:129], v[130:133], v[180:183], v[126:129]
	v_mfma_f32_16x16x32_bf16 v[94:97], v[138:141], v[180:183], v[94:97]
	v_mfma_f32_16x16x32_bf16 v[122:125], v[130:133], v[188:191], v[122:125]
	v_mfma_f32_16x16x32_bf16 v[90:93], v[138:141], v[188:191], v[90:93]
	v_mfma_f32_16x16x32_bf16 v[118:121], v[130:133], v[196:199], v[118:121]
	v_mfma_f32_16x16x32_bf16 v[86:89], v[138:141], v[196:199], v[86:89]
	v_mfma_f32_16x16x32_bf16 v[114:117], v[130:133], v[204:207], v[114:117]
	v_mfma_f32_16x16x32_bf16 v[82:85], v[138:141], v[204:207], v[82:85]
	v_mfma_f32_16x16x32_bf16 v[126:129], v[134:137], v[184:187], v[126:129]
	v_mfma_f32_16x16x32_bf16 v[94:97], v[142:145], v[184:187], v[94:97]
	v_mfma_f32_16x16x32_bf16 v[122:125], v[134:137], v[192:195], v[122:125]
	v_mfma_f32_16x16x32_bf16 v[90:93], v[142:145], v[192:195], v[90:93]
	v_mfma_f32_16x16x32_bf16 v[118:121], v[134:137], v[200:203], v[118:121]
	v_mfma_f32_16x16x32_bf16 v[86:89], v[142:145], v[200:203], v[86:89]
	v_mfma_f32_16x16x32_bf16 v[114:117], v[134:137], v[208:211], v[114:117]
	v_mfma_f32_16x16x32_bf16 v[82:85], v[142:145], v[208:211], v[82:85]
	s_setprio 0
	s_setprio 1
	v_mfma_f32_16x16x32_bf16 v[62:65], v[146:149], v[180:183], v[62:65]
	v_mfma_f32_16x16x32_bf16 v[30:33], v[154:157], v[180:183], v[30:33]
	v_mfma_f32_16x16x32_bf16 v[58:61], v[146:149], v[188:191], v[58:61]
	v_mfma_f32_16x16x32_bf16 v[26:29], v[154:157], v[188:191], v[26:29]
	v_mfma_f32_16x16x32_bf16 v[54:57], v[146:149], v[196:199], v[54:57]
	v_mfma_f32_16x16x32_bf16 v[22:25], v[154:157], v[196:199], v[22:25]
	v_mfma_f32_16x16x32_bf16 v[50:53], v[146:149], v[204:207], v[50:53]
	v_mfma_f32_16x16x32_bf16 v[18:21], v[154:157], v[204:207], v[18:21]
	v_mfma_f32_16x16x32_bf16 v[62:65], v[150:153], v[184:187], v[62:65]
	v_mfma_f32_16x16x32_bf16 v[30:33], v[158:161], v[184:187], v[30:33]
	v_mfma_f32_16x16x32_bf16 v[58:61], v[150:153], v[192:195], v[58:61]
	v_mfma_f32_16x16x32_bf16 v[26:29], v[158:161], v[192:195], v[26:29]
	v_mfma_f32_16x16x32_bf16 v[54:57], v[150:153], v[200:203], v[54:57]
	v_mfma_f32_16x16x32_bf16 v[22:25], v[158:161], v[200:203], v[22:25]
	v_mfma_f32_16x16x32_bf16 v[50:53], v[150:153], v[208:211], v[50:53]
	v_mfma_f32_16x16x32_bf16 v[18:21], v[158:161], v[208:211], v[18:21]
	s_setprio 0
	s_barrier
	s_add_i32 s4, s59, s21
	s_mov_b32 m0, s4
	ds_read_b128 v[180:183], v219 offset:16384
	ds_read_b128 v[184:187], v219 offset:17408
	global_load_lds_dwordx4 v164, s[36:37]
	ds_read_b128 v[188:191], v219 offset:18432
	s_add_i32 m0, s4, 0x2000
	s_add_u32 s4, s36, 0x100000
	s_addc_u32 s5, s37, 0
	s_add_i32 s65, s60, s21
	global_load_lds_dwordx4 v168, s[36:37]
	ds_read_b128 v[192:195], v219 offset:19456
	s_mov_b32 m0, s65
	s_nop 0
	global_load_lds_dwordx4 v164, s[4:5]
	ds_read_b128 v[196:199], v219 offset:20480
	s_add_i32 m0, s65, 0x2000
	s_nop 0
	global_load_lds_dwordx4 v168, s[4:5]
	ds_read_b128 v[200:203], v219 offset:21504
	s_mov_b32 m0, s40
	s_nop 0
	global_load_lds_dwordx4 v162, s[38:39]
	ds_read_b128 v[204:207], v219 offset:22528
	s_mov_b32 m0, s41
	s_nop 0
	global_load_lds_dwordx4 v166, s[38:39]
	ds_read_b128 v[208:211], v219 offset:23552
	s_waitcnt vmcnt(8)
	s_waitcnt lgkmcnt(0)
	s_barrier
	s_setprio 1
	s_waitcnt lgkmcnt(0)
	v_mfma_f32_16x16x32_bf16 v[110:113], v[130:133], v[180:183], v[110:113]
	v_mfma_f32_16x16x32_bf16 v[78:81], v[138:141], v[180:183], v[78:81]
	v_mfma_f32_16x16x32_bf16 v[106:109], v[130:133], v[188:191], v[106:109]
	v_mfma_f32_16x16x32_bf16 v[74:77], v[138:141], v[188:191], v[74:77]
	v_mfma_f32_16x16x32_bf16 v[102:105], v[130:133], v[196:199], v[102:105]
	v_mfma_f32_16x16x32_bf16 v[70:73], v[138:141], v[196:199], v[70:73]
	v_mfma_f32_16x16x32_bf16 v[98:101], v[130:133], v[204:207], v[98:101]
	v_mfma_f32_16x16x32_bf16 v[66:69], v[138:141], v[204:207], v[66:69]
	v_mfma_f32_16x16x32_bf16 v[110:113], v[134:137], v[184:187], v[110:113]
	v_mfma_f32_16x16x32_bf16 v[78:81], v[142:145], v[184:187], v[78:81]
	v_mfma_f32_16x16x32_bf16 v[106:109], v[134:137], v[192:195], v[106:109]
	v_mfma_f32_16x16x32_bf16 v[74:77], v[142:145], v[192:195], v[74:77]
	v_mfma_f32_16x16x32_bf16 v[102:105], v[134:137], v[200:203], v[102:105]
	v_mfma_f32_16x16x32_bf16 v[70:73], v[142:145], v[200:203], v[70:73]
	v_mfma_f32_16x16x32_bf16 v[98:101], v[134:137], v[208:211], v[98:101]
	v_mfma_f32_16x16x32_bf16 v[66:69], v[142:145], v[208:211], v[66:69]
	s_setprio 0
	s_setprio 1
	v_mfma_f32_16x16x32_bf16 v[46:49], v[146:149], v[180:183], v[46:49]
	v_mfma_f32_16x16x32_bf16 v[14:17], v[154:157], v[180:183], v[14:17]
	v_mfma_f32_16x16x32_bf16 v[42:45], v[146:149], v[188:191], v[42:45]
	v_mfma_f32_16x16x32_bf16 v[10:13], v[154:157], v[188:191], v[10:13]
	v_mfma_f32_16x16x32_bf16 v[38:41], v[146:149], v[196:199], v[38:41]
	v_mfma_f32_16x16x32_bf16 v[6:9], v[154:157], v[196:199], v[6:9]
	v_mfma_f32_16x16x32_bf16 v[34:37], v[146:149], v[204:207], v[34:37]
	v_mfma_f32_16x16x32_bf16 v[2:5], v[154:157], v[204:207], v[2:5]
	v_mfma_f32_16x16x32_bf16 v[46:49], v[150:153], v[184:187], v[46:49]
	v_mfma_f32_16x16x32_bf16 v[14:17], v[158:161], v[184:187], v[14:17]
	v_mfma_f32_16x16x32_bf16 v[42:45], v[150:153], v[192:195], v[42:45]
	v_mfma_f32_16x16x32_bf16 v[10:13], v[158:161], v[192:195], v[10:13]
	v_mfma_f32_16x16x32_bf16 v[38:41], v[150:153], v[200:203], v[38:41]
	v_mfma_f32_16x16x32_bf16 v[6:9], v[158:161], v[200:203], v[6:9]
	v_mfma_f32_16x16x32_bf16 v[34:37], v[150:153], v[208:211], v[34:37]
	v_mfma_f32_16x16x32_bf16 v[2:5], v[158:161], v[208:211], v[2:5]
	s_setprio 0
	s_barrier
; #define PG8_STAGE(bufoff, gbase, voff) do { _Pragma("unroll") for (int _i = 0; _i < 2; ++_i) \
;         __builtin_amdgcn_global_load_lds((const unsigned*)((const char*)(gbase) + (voff)[_i]), (LAS unsigned*)(lds + (bufoff) + ldsw + _i * 8192), 16, 0, 0); } while (0)
; #define PG8_LDA(dst, b, h) do { _Pragma("unroll") for (int m = 0; m < 4; ++m) _Pragma("unroll") for (int k = 0; k < 2; ++k) dst[m][k] = *(const LAS bf16x8*)(lds + PG8_SA(b, h) + aoff + m * 2048 + k * 1024); } while (0)
; #define PG8_LDB(dst, b, h) do { _Pragma("unroll") for (int n = 0; n < 2; ++n) _Pragma("unroll") for (int k = 0; k < 2; ++k) dst[n][k] = *(const LAS bf16x8*)(lds + PG8_SB(b, h) + boff + n * 2048 + k * 1024); } while (0)
; #define PG8_MMA(ai, bj, At, Bt) do { __builtin_amdgcn_s_setprio(1); _Pragma("unroll") for (int m = 0; m < 4; ++m) _Pragma("unroll") for (int n = 0; n < 2; ++n) _Pragma("unroll") for (int k = 0; k < 2; ++k) \
;         acc[ai][bj][m][n] = __builtin_amdgcn_mfma_f32_16x16x32_bf16(Bt[n][k], At[m][k], acc[ai][bj][m][n], 0, 0, 0); __builtin_amdgcn_s_setprio(0); } while (0)
; #define PG8_WAIT_V(n) asm volatile("s_waitcnt vmcnt(" #n ")" ::: "memory")
; #define PG8_BAR __builtin_amdgcn_s_barrier()
;     __device__ __forceinline__ void operator()(const f32x4 (&acc)[2][2][4][2], const Unit& u, int wr, int wc, int fr, int fq) const {
;         if (u.pn >= TX0 && u.pn < TQ0) { conv_tile(acc, u, wr, wc, fr, fq); return; }
; template <class Epi, class Sched, bool ALIGN_EPI, class Hook = NoHook>
; __device__ __forceinline__ void gemm_phase(LAS unsigned char* lds, const Gemm g, const Sched& S, const Epi& E, const Hook& H = Hook()) {
;     ...
;             PG8_LDB(B0, 1, 0); PG8_LDB(B1, 1, 1); PG8_SCHED; PG8_LDA(At, 1, 0); PG8_STAGE(PG8_SA(0, 1), a2 + hA, voffA);
;             PG8_WAIT_V(8); PG8_WAIT_L(0); PG8_BAR; PG8_MMA(0, 0, At, B0); PG8_MMA(0, 1, At, B1); PG8_BAR; PG8_SCHED;
;             PG8_LDA(At, 1, 1); PG8_STAGE(PG8_SB(1, 0), b3, voffB); PG8_STAGE(PG8_SB(1, 1), b3 + hB, voffB); PG8_STAGE(PG8_SA(1, 0), a3, voffA);
;             PG8_WAIT_V(8); PG8_WAIT_L(0); PG8_BAR; PG8_MMA(1, 0, At, B0); PG8_MMA(1, 1, At, B1); PG8_BAR; PG8_SCHED;
;         }
;         if constexpr (Hook::ON) H.after(te, acc, cur, wr, wc, fr, fq);
;         }
;         if constexpr (ALIGN_EPI) { if (wr == 0) PG8_BAR; }
;         if constexpr (!Epi::AFTER_DRAIN) { E(acc, cur, wr, wc, fr, fq); S.done(cur); }
	s_add_i32 s65, 0, 0x18000
	s_add_i32 s66, 0, 0x1c000
	v_add_u32_e32 v142, s65, v213
	v_add_u32_e32 v158, s66, v213
	ds_read_b128 v[130:133], v142
	ds_read_b128 v[134:137], v142 offset:1024
	s_add_u32 s4, s38, 0x8000
	s_addc_u32 s5, s39, 0
	s_mov_b32 m0, s42
	s_nop 0
	global_load_lds_dwordx4 v162, s[4:5]
	ds_read_b128 v[138:141], v142 offset:2048
	ds_read_b128 v[142:145], v142 offset:3072
	ds_read_b128 v[146:149], v158
	ds_read_b128 v[150:153], v158 offset:1024
	ds_read_b128 v[154:157], v158 offset:2048
	ds_read_b128 v[158:161], v158 offset:3072
	ds_read_b128 v[180:183], v219 offset:32768
	s_mov_b32 m0, s43
	s_nop 0
	global_load_lds_dwordx4 v166, s[4:5]
	ds_read_b128 v[184:187], v219 offset:33792
	ds_read_b128 v[188:191], v219 offset:34816
	ds_read_b128 v[192:195], v219 offset:35840
	ds_read_b128 v[196:199], v219 offset:36864
	ds_read_b128 v[200:203], v219 offset:37888
	ds_read_b128 v[204:207], v219 offset:38912
	ds_read_b128 v[208:211], v219 offset:39936
	s_waitcnt vmcnt(8)
	s_waitcnt lgkmcnt(0)
	s_barrier
	s_setprio 1
	s_waitcnt lgkmcnt(0)
	v_mfma_f32_16x16x32_bf16 v[126:129], v[130:133], v[180:183], v[126:129]
	v_mfma_f32_16x16x32_bf16 v[94:97], v[138:141], v[180:183], v[94:97]
	v_mfma_f32_16x16x32_bf16 v[122:125], v[130:133], v[188:191], v[122:125]
	v_mfma_f32_16x16x32_bf16 v[90:93], v[138:141], v[188:191], v[90:93]
	v_mfma_f32_16x16x32_bf16 v[118:121], v[130:133], v[196:199], v[118:121]
	v_mfma_f32_16x16x32_bf16 v[86:89], v[138:141], v[196:199], v[86:89]
	v_mfma_f32_16x16x32_bf16 v[114:117], v[130:133], v[204:207], v[114:117]
	v_mfma_f32_16x16x32_bf16 v[82:85], v[138:141], v[204:207], v[82:85]
	v_mfma_f32_16x16x32_bf16 v[126:129], v[134:137], v[184:187], v[126:129]
	v_mfma_f32_16x16x32_bf16 v[94:97], v[142:145], v[184:187], v[94:97]
	v_mfma_f32_16x16x32_bf16 v[122:125], v[134:137], v[192:195], v[122:125]
	v_mfma_f32_16x16x32_bf16 v[90:93], v[142:145], v[192:195], v[90:93]
	v_mfma_f32_16x16x32_bf16 v[118:121], v[134:137], v[200:203], v[118:121]
	v_mfma_f32_16x16x32_bf16 v[86:89], v[142:145], v[200:203], v[86:89]
	v_mfma_f32_16x16x32_bf16 v[114:117], v[134:137], v[208:211], v[114:117]
	v_mfma_f32_16x16x32_bf16 v[82:85], v[142:145], v[208:211], v[82:85]
	s_setprio 0
	s_setprio 1
	v_mfma_f32_16x16x32_bf16 v[62:65], v[146:149], v[180:183], v[62:65]
	v_mfma_f32_16x16x32_bf16 v[30:33], v[154:157], v[180:183], v[30:33]
	v_mfma_f32_16x16x32_bf16 v[58:61], v[146:149], v[188:191], v[58:61]
	v_mfma_f32_16x16x32_bf16 v[26:29], v[154:157], v[188:191], v[26:29]
	v_mfma_f32_16x16x32_bf16 v[54:57], v[146:149], v[196:199], v[54:57]
	v_mfma_f32_16x16x32_bf16 v[22:25], v[154:157], v[196:199], v[22:25]
	v_mfma_f32_16x16x32_bf16 v[50:53], v[146:149], v[204:207], v[50:53]
	v_mfma_f32_16x16x32_bf16 v[18:21], v[154:157], v[204:207], v[18:21]
	v_mfma_f32_16x16x32_bf16 v[62:65], v[150:153], v[184:187], v[62:65]
	v_mfma_f32_16x16x32_bf16 v[30:33], v[158:161], v[184:187], v[30:33]
	v_mfma_f32_16x16x32_bf16 v[58:61], v[150:153], v[192:195], v[58:61]
	v_mfma_f32_16x16x32_bf16 v[26:29], v[158:161], v[192:195], v[26:29]
	v_mfma_f32_16x16x32_bf16 v[54:57], v[150:153], v[200:203], v[54:57]
	v_mfma_f32_16x16x32_bf16 v[22:25], v[158:161], v[200:203], v[22:25]
	v_mfma_f32_16x16x32_bf16 v[50:53], v[150:153], v[208:211], v[50:53]
	v_mfma_f32_16x16x32_bf16 v[18:21], v[158:161], v[208:211], v[18:21]
	s_setprio 0
	s_barrier
	s_add_i32 s4, s65, s21
	s_add_u32 s68, s36, s14
	s_addc_u32 s69, s37, s15
	s_mov_b32 m0, s4
	ds_read_b128 v[180:183], v219 offset:49152
	ds_read_b128 v[184:187], v219 offset:50176
	global_load_lds_dwordx4 v164, s[68:69]
	ds_read_b128 v[188:191], v219 offset:51200
	s_add_i32 m0, s4, 0x2000
	s_add_u32 s4, s36, 0x100080
	s_addc_u32 s5, s37, 0
	s_add_i32 s36, s66, s21
	global_load_lds_dwordx4 v168, s[68:69]
	ds_read_b128 v[192:195], v219 offset:52224
	s_mov_b32 m0, s36
	s_nop 0
	global_load_lds_dwordx4 v164, s[4:5]
	ds_read_b128 v[196:199], v219 offset:53248
	s_add_i32 m0, s36, 0x2000
	s_nop 0
	global_load_lds_dwordx4 v168, s[4:5]
	ds_read_b128 v[200:203], v219 offset:54272
	s_add_u32 s70, s38, s14
	s_addc_u32 s71, s39, s15
	s_mov_b32 m0, s51
	s_nop 0
	global_load_lds_dwordx4 v162, s[70:71]
	ds_read_b128 v[204:207], v219 offset:55296
	s_mov_b32 m0, s52
	s_nop 0
	global_load_lds_dwordx4 v166, s[70:71]
	ds_read_b128 v[208:211], v219 offset:56320
	s_waitcnt vmcnt(8)
	s_waitcnt lgkmcnt(0)
	s_barrier
	s_setprio 1
	s_waitcnt lgkmcnt(0)
	v_mfma_f32_16x16x32_bf16 v[110:113], v[130:133], v[180:183], v[110:113]
	v_mfma_f32_16x16x32_bf16 v[78:81], v[138:141], v[180:183], v[78:81]
	v_mfma_f32_16x16x32_bf16 v[106:109], v[130:133], v[188:191], v[106:109]
	v_mfma_f32_16x16x32_bf16 v[74:77], v[138:141], v[188:191], v[74:77]
	v_mfma_f32_16x16x32_bf16 v[102:105], v[130:133], v[196:199], v[102:105]
	v_mfma_f32_16x16x32_bf16 v[70:73], v[138:141], v[196:199], v[70:73]
	v_mfma_f32_16x16x32_bf16 v[98:101], v[130:133], v[204:207], v[98:101]
	v_mfma_f32_16x16x32_bf16 v[66:69], v[138:141], v[204:207], v[66:69]
	v_mfma_f32_16x16x32_bf16 v[110:113], v[134:137], v[184:187], v[110:113]
	v_mfma_f32_16x16x32_bf16 v[78:81], v[142:145], v[184:187], v[78:81]
	v_mfma_f32_16x16x32_bf16 v[106:109], v[134:137], v[192:195], v[106:109]
	v_mfma_f32_16x16x32_bf16 v[74:77], v[142:145], v[192:195], v[74:77]
	v_mfma_f32_16x16x32_bf16 v[102:105], v[134:137], v[200:203], v[102:105]
	v_mfma_f32_16x16x32_bf16 v[70:73], v[142:145], v[200:203], v[70:73]
	v_mfma_f32_16x16x32_bf16 v[98:101], v[134:137], v[208:211], v[98:101]
	v_mfma_f32_16x16x32_bf16 v[66:69], v[142:145], v[208:211], v[66:69]
	s_setprio 0
	s_setprio 1
	v_mfma_f32_16x16x32_bf16 v[46:49], v[146:149], v[180:183], v[46:49]
	v_mfma_f32_16x16x32_bf16 v[14:17], v[154:157], v[180:183], v[14:17]
	v_mfma_f32_16x16x32_bf16 v[42:45], v[146:149], v[188:191], v[42:45]
	v_mfma_f32_16x16x32_bf16 v[10:13], v[154:157], v[188:191], v[10:13]
	v_mfma_f32_16x16x32_bf16 v[38:41], v[146:149], v[196:199], v[38:41]
	v_mfma_f32_16x16x32_bf16 v[6:9], v[154:157], v[196:199], v[6:9]
	v_mfma_f32_16x16x32_bf16 v[34:37], v[146:149], v[204:207], v[34:37]
	v_mfma_f32_16x16x32_bf16 v[2:5], v[154:157], v[204:207], v[2:5]
	v_mfma_f32_16x16x32_bf16 v[46:49], v[150:153], v[184:187], v[46:49]
	v_mfma_f32_16x16x32_bf16 v[14:17], v[158:161], v[184:187], v[14:17]
	v_mfma_f32_16x16x32_bf16 v[42:45], v[150:153], v[192:195], v[42:45]
	v_mfma_f32_16x16x32_bf16 v[10:13], v[158:161], v[192:195], v[10:13]
	v_mfma_f32_16x16x32_bf16 v[38:41], v[150:153], v[200:203], v[38:41]
	v_mfma_f32_16x16x32_bf16 v[6:9], v[158:161], v[200:203], v[6:9]
	v_mfma_f32_16x16x32_bf16 v[34:37], v[150:153], v[208:211], v[34:37]
	v_mfma_f32_16x16x32_bf16 v[2:5], v[158:161], v[208:211], v[2:5]
	s_setprio 0
	s_barrier
	s_add_i32 s64, s64, 2
	s_add_u32 s31, s31, 0x100
	s_addc_u32 s63, s63, 0
	s_cmp_gt_u32 s64, 61
	s_mov_b64 s[4:5], s[34:35]
	s_cbranch_scc0 .Lmy_d199B
.Lmy_d199X:
	s_and_b64 vcc, exec, s[18:19]
	s_cbranch_vccz .LBB0_203
	s_barrier
	s_sub_i32 s4, s6, 32
	s_cmp_gt_u32 s4, 39
	s_mov_b64 s[4:5], -1
	s_cbranch_scc1 .LBB0_204
